# phase X compressed-attention pass 1: next key tile prefetched into spare registers right after the QK MFMAs (the loop top no longer waits on a just-issued load)
# baseline (speedup 1.0000x reference)
; #define NEGINF (-__builtin_inff())
; DI float shx32(float v) { const auto r = __builtin_amdgcn_permlane32_swap(__float_as_uint(v), __float_as_uint(v), false, false); return __uint_as_float((threadIdx.x & 32) ? r[0] : r[1]); }
; DI float ex2(float x) { return __builtin_amdgcn_exp2f(x); }
; DI int crow(int i, int h) { return (i & 3) + 8 * (i >> 2) + 4 * h; }
; DI void nsa_cmp_item(const Params& p, int item, const unsigned char* blut, const float* tbl, float* impw) {
;     ...
;     for (int kt = 0; kt < ntile; ++kt) {
;       const f32x16 s = qk_tile(qf, KC + (size_t)kt * 2048 + (h * 32 + r) * 8);
;       float lg[16]; float mx = NEGINF;
;       int dist[16]; float bv[16];
; #pragma unroll
;       for (int i = 0; i < 16; ++i) dist[i] = t - (16 * (kt * 32 + crow(i, h)) + 31);
;       bias16(blut, tblh, dist, bv);
; #pragma unroll
;       for (int i = 0; i < 16; ++i) { lg[i] = (dist[i] >= 0) ? s[i] + bv[i] : NEGINF; mx = fmaxf(mx, lg[i]); }
;       mx = fmaxf(mx, shx32(mx));
;       const float mnew = fmaxf(m, mx), muse = (mnew == NEGINF) ? 0.f : mnew;
;       float rs = 0.f;
; #pragma unroll
;       for (int i = 0; i < 16; ++i) rs += ex2(lg[i] - muse);
;       l = l * ex2(m - muse) + rs; m = mnew;
;     }
.LBB0_162:
	v_add_u32_e32 v93, s23, v89
	v_lshlrev_b32_e32 v130, 7, v93
	v_lshl_add_u64 v[0:1], v[74:75], 0, v[130:131]
	global_load_dwordx4 v[48:51], v[0:1], off
	global_load_dwordx4 v[52:55], v[0:1], off offset:32
	global_load_dwordx4 v[56:59], v[0:1], off offset:64
	global_load_dwordx4 v[60:63], v[0:1], off offset:96
	v_add_u32_e32 v94, 0, v130
	v_lshlrev_b32_e32 v82, 6, v93
	v_mov_b32_e32 v18, 0
	v_mov_b32_e32 v21, 0xff800000
	s_mov_b64 s[14:15], 0
	v_mov_b64_e32 v[16:17], v[72:73]
	v_mov_b32_e32 v19, v91
	v_mov_b32_e32 v20, v90
	global_load_dwordx4 v[156:159], v[16:17], off
	global_load_dwordx4 v[160:163], v[16:17], off offset:1024
	global_load_dwordx4 v[164:167], v[16:17], off offset:2048
	global_load_dwordx4 v[168:171], v[16:17], off offset:3072
.LBB0_163:
	v_add_u32_e32 v34, 0x1b0, v19
	v_add_u32_e32 v35, 0x1a0, v19
	v_add_u32_e32 v36, 0x190, v19
	v_add_u32_e32 v37, 0x180, v19
	v_add_u32_e32 v38, 0x130, v19
	v_add_u32_e32 v39, 0x120, v19
	v_add_u32_e32 v40, 0x110, v19
	v_add_u32_e32 v41, 0x100, v19
	v_add_u32_e32 v42, 0xb0, v19
	v_add_u32_e32 v43, 0xa0, v19
	v_add_u32_e32 v44, 0x90, v19
	v_add_u32_e32 v45, 0x80, v19
	v_add_u32_e32 v46, 48, v19
	v_add_u32_e32 v47, 32, v19
	v_add_u32_e32 v84, 16, v19
	v_med3_i32 v85, v46, 0, v198
	v_med3_i32 v95, v47, 0, v198
	s_waitcnt vmcnt(16)
	v_med3_i32 v96, v84, 0, v198
	v_med3_i32 v97, v19, 0, v198
	v_add_u32_e32 v85, 0, v85
	v_add_u32_e32 v95, 0, v95
	v_add_u32_e32 v96, 0, v96
	v_add_u32_e32 v97, 0, v97
	v_cmp_lt_i32_e32 vcc, -1, v34
	v_add_u32_e32 v20, -1, v20
	v_lshl_add_u64 v[16:17], v[16:17], 0, s[80:81]
	s_waitcnt vmcnt(0)
	v_mfma_f32_32x32x16_bf16 v[0:15], v[156:159], v[48:51], 0
	ds_read_u8 v85, v85
	ds_read_u8 v95, v95
	ds_read_u8 v96, v96
	ds_read_u8 v97, v97
	s_nop 0
	v_mfma_f32_32x32x16_bf16 v[0:15], v[160:163], v[52:55], v[0:15]
	v_med3_i32 v22, v34, 0, v198
	v_med3_i32 v23, v35, 0, v198
	v_med3_i32 v24, v36, 0, v198
	v_med3_i32 v25, v37, 0, v198
	v_add_u32_e32 v22, 0, v22
	v_add_u32_e32 v23, 0, v23
	v_add_u32_e32 v24, 0, v24
	s_nop 0
	v_mfma_f32_32x32x16_bf16 v[0:15], v[164:167], v[56:59], v[0:15]
	v_med3_i32 v26, v38, 0, v198
	v_med3_i32 v27, v39, 0, v198
	v_med3_i32 v28, v40, 0, v198
	v_med3_i32 v29, v41, 0, v198
	v_add_u32_e32 v25, 0, v25
	v_add_u32_e32 v26, 0, v26
	v_add_u32_e32 v27, 0, v27
	s_nop 0
	v_mfma_f32_32x32x16_bf16 v[0:15], v[168:171], v[60:63], v[0:15]
	global_load_dwordx4 v[156:159], v[16:17], off
	global_load_dwordx4 v[160:163], v[16:17], off offset:1024
	global_load_dwordx4 v[164:167], v[16:17], off offset:2048
	global_load_dwordx4 v[168:171], v[16:17], off offset:3072
	v_med3_i32 v30, v42, 0, v198
	v_med3_i32 v31, v43, 0, v198
	v_med3_i32 v32, v44, 0, v198
	v_med3_i32 v33, v45, 0, v198
	v_add_u32_e32 v28, 0, v28
	v_add_u32_e32 v29, 0, v29
	v_add_u32_e32 v30, 0, v30
	v_add_u32_e32 v31, 0, v31
	v_add_u32_e32 v32, 0, v32
	v_add_u32_e32 v33, 0, v33
	ds_read_u8 v22, v22
	ds_read_u8 v23, v23
	ds_read_u8 v24, v24
	ds_read_u8 v25, v25
	ds_read_u8 v26, v26
	ds_read_u8 v27, v27
	ds_read_u8 v28, v28
	ds_read_u8 v29, v29
	ds_read_u8 v30, v30
	ds_read_u8 v31, v31
	ds_read_u8 v32, v32
	ds_read_u8 v33, v33
	s_waitcnt lgkmcnt(11)
	s_waitcnt lgkmcnt(10)
	s_waitcnt lgkmcnt(9)
	s_waitcnt lgkmcnt(8)
	s_waitcnt lgkmcnt(7)
	s_waitcnt lgkmcnt(6)
	s_waitcnt lgkmcnt(5)
	s_waitcnt lgkmcnt(4)
	s_waitcnt lgkmcnt(3)
	s_waitcnt lgkmcnt(2)
	s_waitcnt lgkmcnt(1)
	s_waitcnt lgkmcnt(0)
	v_lshl_add_u32 v22, v22, 2, v94
	v_lshl_add_u32 v23, v23, 2, v94
	v_lshl_add_u32 v24, v24, 2, v94
	v_lshl_add_u32 v25, v25, 2, v94
	v_lshl_add_u32 v26, v26, 2, v94
	v_lshl_add_u32 v27, v27, 2, v94
	v_lshl_add_u32 v28, v28, 2, v94
	v_lshl_add_u32 v29, v29, 2, v94
	v_lshl_add_u32 v30, v30, 2, v94
	v_lshl_add_u32 v31, v31, 2, v94
	v_lshl_add_u32 v32, v32, 2, v94
	v_lshl_add_u32 v33, v33, 2, v94
	v_lshl_add_u32 v85, v85, 2, v94
	v_lshl_add_u32 v95, v95, 2, v94
	v_lshl_add_u32 v96, v96, 2, v94
	v_lshl_add_u32 v97, v97, 2, v94
	ds_read_b32 v22, v22 offset:4096
	ds_read_b32 v23, v23 offset:4096
	ds_read_b32 v24, v24 offset:4096
	ds_read_b32 v25, v25 offset:4096
	ds_read_b32 v26, v26 offset:4096
	ds_read_b32 v27, v27 offset:4096
	ds_read_b32 v28, v28 offset:4096
	ds_read_b32 v29, v29 offset:4096
	ds_read_b32 v30, v30 offset:4096
	ds_read_b32 v31, v31 offset:4096
	ds_read_b32 v32, v32 offset:4096
	ds_read_b32 v33, v33 offset:4096
	ds_read_b32 v85, v85 offset:4096
	ds_read_b32 v95, v95 offset:4096
	ds_read_b32 v96, v96 offset:4096
	ds_read_b32 v97, v97 offset:4096
	s_waitcnt lgkmcnt(14)
	s_waitcnt lgkmcnt(13)
	s_waitcnt lgkmcnt(12)
	s_waitcnt lgkmcnt(11)
	s_waitcnt lgkmcnt(10)
	v_add_f32_e32 v0, v0, v22
	v_cndmask_b32_e32 v22, v199, v0, vcc
	v_cmp_lt_i32_e32 vcc, -1, v35
	v_add_f32_e32 v0, v1, v23
	v_add_f32_e32 v2, v2, v24
	v_cndmask_b32_e32 v1, v199, v0, vcc
	v_cmp_lt_i32_e32 vcc, -1, v36
	v_add_f32_e32 v3, v3, v25
	v_add_f32_e32 v4, v4, v26
	v_cndmask_b32_e32 v2, v199, v2, vcc
	v_cmp_lt_i32_e32 vcc, -1, v37
	v_add_f32_e32 v5, v5, v27
	s_waitcnt lgkmcnt(9)
	s_waitcnt lgkmcnt(8)
; #define NEGINF (-__builtin_inff())
; DI float shx32(float v) { const auto r = __builtin_amdgcn_permlane32_swap(__float_as_uint(v), __float_as_uint(v), false, false); return __uint_as_float((threadIdx.x & 32) ? r[0] : r[1]); }
; DI float ex2(float x) { return __builtin_amdgcn_exp2f(x); }
; DI void nsa_cmp_item(const Params& p, int item, const unsigned char* blut, const float* tbl, float* impw) {
;     ...
;       for (int i = 0; i < 16; ++i) { lg[i] = (dist[i] >= 0) ? s[i] + bv[i] : NEGINF; mx = fmaxf(mx, lg[i]); }
;       mx = fmaxf(mx, shx32(mx));
;       const float mnew = fmaxf(m, mx), muse = (mnew == NEGINF) ? 0.f : mnew;
;       float rs = 0.f;
; #pragma unroll
;       for (int i = 0; i < 16; ++i) rs += ex2(lg[i] - muse);
;       l = l * ex2(m - muse) + rs; m = mnew;
;     }
;     l += shx32(l);
;     const float muse = (m == NEGINF) ? 0.f : m;
;     const float inv = (l > 0.f) ? 1.f / l : 0.f;
;     AttnSt st; attn_init(st);
	s_waitcnt lgkmcnt(7)
	s_waitcnt lgkmcnt(6)
	v_cndmask_b32_e32 v3, v199, v3, vcc
	v_cmp_lt_i32_e32 vcc, -1, v38
	v_add_f32_e32 v6, v6, v28
	v_add_f32_e32 v7, v7, v29
	v_cndmask_b32_e32 v4, v199, v4, vcc
	v_cmp_lt_i32_e32 vcc, -1, v39
	v_add_f32_e32 v8, v8, v30
	v_add_f32_e32 v9, v9, v31
	v_cndmask_b32_e32 v5, v199, v5, vcc
	v_cmp_lt_i32_e32 vcc, -1, v40
	s_waitcnt lgkmcnt(5)
	v_max3_f32 v0, v22, s5, v1
	v_add_f32_e32 v10, v10, v32
	v_cndmask_b32_e32 v6, v199, v6, vcc
	v_cmp_lt_i32_e32 vcc, -1, v41
	s_waitcnt lgkmcnt(4)
	v_max3_f32 v0, v0, v2, v3
	v_add_f32_e32 v11, v11, v33
	v_cndmask_b32_e32 v7, v199, v7, vcc
	v_cmp_lt_i32_e32 vcc, -1, v42
	s_waitcnt lgkmcnt(3)
	v_max3_f32 v0, v0, v4, v5
	v_add_f32_e32 v12, v12, v85
	v_cndmask_b32_e32 v8, v199, v8, vcc
	v_cmp_lt_i32_e32 vcc, -1, v43
	s_waitcnt lgkmcnt(2)
	v_max3_f32 v0, v0, v6, v7
	v_add_f32_e32 v13, v13, v95
	v_cndmask_b32_e32 v9, v199, v9, vcc
	v_cmp_lt_i32_e32 vcc, -1, v44
	s_waitcnt lgkmcnt(1)
	v_max3_f32 v0, v0, v8, v9
	v_add_f32_e32 v14, v14, v96
	v_cndmask_b32_e32 v10, v199, v10, vcc
	v_cmp_lt_i32_e32 vcc, -1, v45
	s_waitcnt lgkmcnt(0)
	s_nop 0
	v_add_f32_e32 v15, v15, v97
	v_cndmask_b32_e32 v11, v199, v11, vcc
	v_cmp_lt_i32_e32 vcc, -1, v46
	v_max3_f32 v0, v0, v10, v11
	s_nop 0
	v_cndmask_b32_e32 v12, v199, v12, vcc
	v_cmp_lt_i32_e32 vcc, -1, v47
	s_nop 1
	v_cndmask_b32_e32 v13, v199, v13, vcc
	v_cmp_lt_i32_e32 vcc, -1, v84
	v_max3_f32 v0, v0, v12, v13
	s_nop 0
	v_cndmask_b32_e32 v14, v199, v14, vcc
	v_cmp_lt_i32_e32 vcc, -1, v19
	v_add_u32_e32 v19, 0xfffffe00, v19
	s_nop 0
	v_cndmask_b32_e32 v15, v199, v15, vcc
	v_max3_f32 v0, v0, v14, v15
	v_mov_b32_e32 v23, v0
	v_mov_b32_e32 v24, v0
	s_nop 1
	v_permlane32_swap_b32_e32 v23, v24
	v_cndmask_b32_e64 v23, v23, v24, s[12:13]
	v_max3_f32 v0, v21, v0, v23
	v_cmp_neq_f32_e32 vcc, s5, v0
	s_nop 1
	v_cndmask_b32_e32 v95, 0, v0, vcc
	v_sub_f32_e32 v22, v22, v95
	v_exp_f32_e32 v22, v22
	v_sub_f32_e32 v1, v1, v95
	v_exp_f32_e32 v1, v1
	v_sub_f32_e32 v2, v2, v95
	v_exp_f32_e32 v2, v2
	v_add_f32_e32 v22, 0, v22
	v_add_f32_e32 v1, v1, v22
	v_cmp_eq_u32_e32 vcc, 0, v20
	v_add_f32_e32 v1, v2, v1
	v_sub_f32_e32 v2, v3, v95
	v_exp_f32_e32 v2, v2
	v_mov_b32_e32 v3, v18
	s_or_b64 s[14:15], vcc, s[14:15]
	v_add_f32_e32 v1, v2, v1
	v_sub_f32_e32 v2, v4, v95
	v_exp_f32_e32 v2, v2
	s_nop 0
	v_add_f32_e32 v1, v2, v1
	v_sub_f32_e32 v2, v5, v95
	v_exp_f32_e32 v2, v2
	s_nop 0
	v_add_f32_e32 v1, v2, v1
	v_sub_f32_e32 v2, v6, v95
	v_exp_f32_e32 v2, v2
	s_nop 0
	v_add_f32_e32 v1, v2, v1
	v_sub_f32_e32 v2, v7, v95
	v_exp_f32_e32 v2, v2
	s_nop 0
	v_add_f32_e32 v1, v2, v1
	v_sub_f32_e32 v2, v8, v95
	v_exp_f32_e32 v2, v2
	s_nop 0
	v_add_f32_e32 v1, v2, v1
	v_sub_f32_e32 v2, v9, v95
	v_exp_f32_e32 v2, v2
	s_nop 0
	v_add_f32_e32 v1, v2, v1
	v_sub_f32_e32 v2, v10, v95
	v_exp_f32_e32 v2, v2
	s_nop 0
	v_add_f32_e32 v1, v2, v1
	v_sub_f32_e32 v2, v11, v95
	v_exp_f32_e32 v2, v2
	s_nop 0
	v_add_f32_e32 v1, v2, v1
	v_sub_f32_e32 v2, v12, v95
	v_exp_f32_e32 v2, v2
	s_nop 0
	v_add_f32_e32 v1, v2, v1
	v_sub_f32_e32 v2, v13, v95
	v_exp_f32_e32 v2, v2
	s_nop 0
	v_add_f32_e32 v1, v2, v1
	v_sub_f32_e32 v2, v14, v95
	v_exp_f32_e32 v2, v2
	s_nop 0
	v_add_f32_e32 v1, v2, v1
	v_sub_f32_e32 v2, v15, v95
	v_exp_f32_e32 v2, v2
	s_nop 0
	v_add_f32_e32 v1, v2, v1
	v_sub_f32_e32 v2, v21, v95
	v_exp_f32_e32 v2, v2
	v_mov_b32_e32 v18, v1
	v_mov_b32_e32 v21, v0
	v_fmac_f32_e32 v18, v3, v2
	s_andn2_b64 exec, exec, s[14:15]
	s_cbranch_execnz .LBB0_163
	s_or_b64 exec, exec, s[14:15]
	v_mov_b32_e32 v0, v18
	v_mov_b32_e32 v1, v18
	s_nop 1
	v_permlane32_swap_b32_e32 v0, v1
	v_cndmask_b32_e64 v0, v0, v1, s[12:13]
	v_add_f32_e32 v0, v18, v0
	v_div_scale_f32 v1, s[14:15], v0, v0, 1.0
	v_rcp_f32_e32 v2, v1
	v_mov_b32_e32 v103, 0
	s_mov_b64 s[14:15], 0
	v_mov_b64_e32 v[84:85], v[80:81]
	v_fma_f32 v3, -v1, v2, 1.0
	v_fmac_f32_e32 v2, v3, v2
	v_div_scale_f32 v3, vcc, 1.0, v0, 1.0
	v_mul_f32_e32 v4, v3, v2
	v_fma_f32 v5, -v1, v4, v3
	v_fmac_f32_e32 v4, v5, v2
	v_fma_f32 v1, -v1, v4, v3
	v_div_fmas_f32 v1, v1, v2, v4
	v_div_fixup_f32 v1, v1, v0, 1.0
	v_cmp_lt_f32_e32 vcc, 0, v0
	v_mov_b32_e32 v97, v91
	v_mov_b32_e32 v98, v92
	v_cndmask_b32_e32 v96, 0, v1, vcc
	v_mov_b32_e32 v99, v90
	v_mov_b32_e32 v0, 0
	v_mov_b32_e32 v1, v103
	v_mov_b32_e32 v2, v103
	v_mov_b32_e32 v3, v103
	v_mov_b32_e32 v4, v103
	v_mov_b32_e32 v5, v103
	v_mov_b32_e32 v6, v103
	v_mov_b32_e32 v7, v103
	v_mov_b32_e32 v8, v103
	v_mov_b32_e32 v9, v103
	v_mov_b32_e32 v10, v103
	v_mov_b32_e32 v11, v103
	v_mov_b32_e32 v12, v103
	v_mov_b32_e32 v13, v103
	v_mov_b32_e32 v14, v103
	v_mov_b32_e32 v15, v103
	v_mov_b32_e32 v16, 0
	v_mov_b32_e32 v17, v103
	v_mov_b32_e32 v18, v103
	v_mov_b32_e32 v19, v103
	v_mov_b32_e32 v20, v103
	v_mov_b32_e32 v21, v103
	v_mov_b32_e32 v22, v103
	v_mov_b32_e32 v23, v103
	v_mov_b32_e32 v24, v103
	v_mov_b32_e32 v25, v103
	v_mov_b32_e32 v26, v103
	v_mov_b32_e32 v27, v103
	v_mov_b32_e32 v28, v103
	v_mov_b32_e32 v29, v103
	v_mov_b32_e32 v30, v103
	v_mov_b32_e32 v31, v103
